# sample attention: V-row cache lines touched while the K row is loaded for the scores, so the later sample_pv loads hit L2 instead of HBM
# speedup vs baseline: 1.0034x; 1.0034x over previous
; __device__ __forceinline__ void sample_scores(const float* base, const bf16_t* Pnew, int pcol, int count, const LAS int* koff, const LAS float* qv, LAS float* sc, int tid) {
;     ...
;         float d0 = -INFINITY, d1 = -INFINITY, d2 = -INFINITY, d3 = -INFINITY;
;         if (ko != KOFF_INVALID) {
;             f32x4 kx[16];
;             if (ko >= 0) {
; #pragma unroll
;                 for (int j = 0; j < 16; ++j) kx[j] = *(const f32x4*)(base + (size_t)ko + 4 * j); }
; __device__ __forceinline__ void sample_pv(const float* base, const bf16_t* Pnew, int pcol, int count, const LAS int* koff, const LAS float* sc, LAS float* part, LAS float* oacc, int tid) {
;     ...
;         if (ko >= 0) v = *(const f32x4*)(base + (size_t)ko + 256 + 4 * dq);
.LBB0_909:
	s_andn2_saveexec_b64 s[22:23], s[22:23]
	s_cbranch_execz .LBB0_904
	v_lshl_add_u64 v[22:23], v[98:99], 2, s[68:69]
	global_load_dword v202, v[22:23], off offset:1024
	global_load_dword v203, v[22:23], off offset:1152
	global_load_dwordx4 v[50:53], v[22:23], off offset:48
	global_load_dwordx4 v[58:61], v[22:23], off offset:32
	global_load_dwordx4 v[62:65], v[22:23], off offset:16
	global_load_dwordx4 v[66:69], v[22:23], off
	global_load_dwordx4 v[34:37], v[22:23], off offset:112
	global_load_dwordx4 v[38:41], v[22:23], off offset:96
	global_load_dwordx4 v[46:49], v[22:23], off offset:80
	global_load_dwordx4 v[54:57], v[22:23], off offset:64
	global_load_dwordx4 v[10:13], v[22:23], off offset:176
	global_load_dwordx4 v[18:21], v[22:23], off offset:160
	global_load_dwordx4 v[26:29], v[22:23], off offset:144
	global_load_dwordx4 v[30:33], v[22:23], off offset:128
	global_load_dwordx4 v[2:5], v[22:23], off offset:240
	global_load_dwordx4 v[6:9], v[22:23], off offset:224
	global_load_dwordx4 v[14:17], v[22:23], off offset:208
	s_nop 0
	global_load_dwordx4 v[22:25], v[22:23], off offset:192
	s_branch .LBB0_904
